# GEMM accumulator zeroing with 64 v_mov_b64 instead of 128 v_mov_b32 per unit (all three K-loop preheaders)
# speedup vs baseline: 1.0098x; 1.0010x over previous
; template <class Epi, class Sched, bool ALIGN_EPI = false, bool SP2 = false>
; __device__ __forceinline__ void gemm_phase(PG8_LAS unsigned char* lds, const Gemm g, const Sched& S, const Epi& E) {
;     ...
;     f32x4 acc[2][2][4][2];
; #pragma unroll
;     for (int a = 0; a < 2; ++a)
; #pragma unroll
;         for (int b = 0; b < 2; ++b)
; #pragma unroll
;             for (int m = 0; m < 4; ++m)
; #pragma unroll
;                 for (int n = 0; n < 2; ++n) acc[a][b][m][n] = (f32x4){0.f, 0.f, 0.f, 0.f};
;     bf16x8 At[4][2], B0[2][2], B1[2][2];
;     const char* cA = (const char*)g.A + (size_t)cur.pm * tstep; const char* cB = (const char*)g.Bt + (size_t)cur.pn * tstep;
;     ...
; #pragma unroll
;         for (int a = 0; a < 2; ++a)
; #pragma unroll
;             for (int b = 0; b < 2; ++b)
; #pragma unroll
;                 for (int m = 0; m < 4; ++m)
; #pragma unroll
;                     for (int n = 0; n < 2; ++n) acc[a][b][m][n] = (f32x4){0.f, 0.f, 0.f, 0.f};
;         cur = nxt; cA = nA; cB = nB; ++ui;
.LBB0_416:
	s_ashr_i32 s43, s42, 31
	s_lshl_b64 s[0:1], s[42:43], 20
	v_readlane_b32 s4, v254, 59
	v_readlane_b32 s5, v254, 60
	s_add_u32 s56, s4, s0
	s_addc_u32 s57, s5, s1
	s_and_b64 s[0:1], s[38:39], exec
	s_cselect_b32 s7, s57, s65
	s_cselect_b32 s8, s56, s64
	s_ashr_i32 s37, s36, 31
	s_lshl_b64 s[0:1], s[36:37], 20
	s_add_u32 s62, s59, s0
	s_addc_u32 s63, s66, s1
	s_and_b64 s[0:1], s[38:39], exec
	s_cselect_b32 s9, s63, s41
	s_cselect_b32 s14, s62, s40
	s_add_u32 s15, s40, 0x100
	s_addc_u32 s17, s41, 0
	s_add_u32 s40, s64, 0x80080
	v_mov_b32_e32 v0, 0
	s_addc_u32 s41, s65, 0
	s_mov_b32 s19, -2
	v_mov_b32_e32 v1, v0
	v_mov_b64_e32 v[2:3], 0
	v_mov_b64_e32 v[4:5], 0
	v_mov_b64_e32 v[6:7], 0
	v_mov_b64_e32 v[16:17], 0
	v_mov_b64_e32 v[18:19], 0
	v_mov_b64_e32 v[20:21], 0
	v_mov_b64_e32 v[22:23], 0
	v_mov_b64_e32 v[32:33], 0
	v_mov_b64_e32 v[34:35], 0
	v_mov_b64_e32 v[36:37], 0
	v_mov_b64_e32 v[38:39], 0
	v_mov_b64_e32 v[48:49], 0
	v_mov_b64_e32 v[50:51], 0
	v_mov_b64_e32 v[52:53], 0
	v_mov_b64_e32 v[54:55], 0
	v_mov_b64_e32 v[8:9], 0
	v_mov_b64_e32 v[10:11], 0
	v_mov_b64_e32 v[12:13], 0
	v_mov_b64_e32 v[14:15], 0
	v_mov_b64_e32 v[24:25], 0
	v_mov_b64_e32 v[26:27], 0
	v_mov_b64_e32 v[28:29], 0
	v_mov_b64_e32 v[30:31], 0
	v_mov_b64_e32 v[40:41], 0
	v_mov_b64_e32 v[42:43], 0
	v_mov_b64_e32 v[44:45], 0
	v_mov_b64_e32 v[46:47], 0
	v_mov_b64_e32 v[56:57], 0
	v_mov_b64_e32 v[58:59], 0
	v_mov_b64_e32 v[60:61], 0
	v_mov_b64_e32 v[62:63], 0
	v_mov_b64_e32 v[64:65], 0
	v_mov_b64_e32 v[66:67], 0
	v_mov_b64_e32 v[68:69], 0
	v_mov_b64_e32 v[70:71], 0
	v_mov_b64_e32 v[80:81], 0
	v_mov_b64_e32 v[82:83], 0
	v_mov_b64_e32 v[84:85], 0
	v_mov_b64_e32 v[86:87], 0
	v_mov_b64_e32 v[98:99], 0
	v_mov_b64_e32 v[100:101], 0
	v_mov_b64_e32 v[102:103], 0
	v_mov_b64_e32 v[104:105], 0
	v_mov_b64_e32 v[114:115], 0
	v_mov_b64_e32 v[116:117], 0
	v_mov_b64_e32 v[118:119], 0
	v_mov_b64_e32 v[120:121], 0
	v_mov_b64_e32 v[72:73], 0
	v_mov_b64_e32 v[74:75], 0
	v_mov_b64_e32 v[76:77], 0
	v_mov_b64_e32 v[78:79], 0
	v_mov_b64_e32 v[88:89], 0
	v_mov_b64_e32 v[90:91], 0
	v_mov_b64_e32 v[92:93], 0
	v_mov_b64_e32 v[94:95], 0
	v_mov_b64_e32 v[106:107], 0
	v_mov_b64_e32 v[108:109], 0
	v_mov_b64_e32 v[110:111], 0
	v_mov_b64_e32 v[112:113], 0
	v_mov_b64_e32 v[122:123], 0
	v_mov_b64_e32 v[124:125], 0
	v_mov_b64_e32 v[126:127], 0
	v_mov_b64_e32 v[128:129], 0

; template <class Epi, class Sched, bool ALIGN_EPI = false, bool SP2 = false>
; __device__ __forceinline__ void gemm_phase(PG8_LAS unsigned char* lds, const Gemm g, const Sched& S, const Epi& E) {
;     ...
; #pragma unroll
;         for (int a = 0; a < 2; ++a)
; #pragma unroll
;             for (int b = 0; b < 2; ++b)
; #pragma unroll
;                 for (int m = 0; m < 4; ++m)
; #pragma unroll
;                     for (int n = 0; n < 2; ++n) acc[a][b][m][n] = (f32x4){0.f, 0.f, 0.f, 0.f};
;         cur = nxt; cA = nA; cB = nB; ++ui;
.LBB0_446:
	s_add_u32 s17, s66, 0x100
	s_addc_u32 s23, s67, 0
	s_add_u32 s66, s68, 0x80
	v_mov_b32_e32 v0, 0
	s_addc_u32 s67, s69, 0
	s_mov_b32 s0, 0
	s_waitcnt lgkmcnt(0)
	v_mov_b32_e32 v1, v0
	v_mov_b64_e32 v[2:3], 0
	v_mov_b64_e32 v[4:5], 0
	v_mov_b64_e32 v[6:7], 0
	v_mov_b64_e32 v[16:17], 0
	v_mov_b64_e32 v[18:19], 0
	v_mov_b64_e32 v[20:21], 0
	v_mov_b64_e32 v[22:23], 0
	v_mov_b64_e32 v[32:33], 0
	v_mov_b64_e32 v[34:35], 0
	v_mov_b64_e32 v[36:37], 0
	v_mov_b64_e32 v[38:39], 0
	v_mov_b64_e32 v[48:49], 0
	v_mov_b64_e32 v[50:51], 0
	v_mov_b64_e32 v[52:53], 0
	v_mov_b64_e32 v[54:55], 0
	v_mov_b64_e32 v[8:9], 0
	v_mov_b64_e32 v[10:11], 0
	v_mov_b64_e32 v[12:13], 0
	v_mov_b64_e32 v[14:15], 0
	v_mov_b64_e32 v[24:25], 0
	v_mov_b64_e32 v[26:27], 0
	v_mov_b64_e32 v[28:29], 0
	v_mov_b64_e32 v[30:31], 0
	v_mov_b64_e32 v[40:41], 0
	v_mov_b64_e32 v[42:43], 0
	v_mov_b64_e32 v[44:45], 0
	v_mov_b64_e32 v[46:47], 0
	v_mov_b64_e32 v[56:57], 0
	v_mov_b64_e32 v[58:59], 0
	v_mov_b64_e32 v[60:61], 0
	v_mov_b64_e32 v[62:63], 0
	v_mov_b64_e32 v[64:65], 0
	v_mov_b64_e32 v[66:67], 0
	v_mov_b64_e32 v[68:69], 0
	v_mov_b64_e32 v[70:71], 0
	v_mov_b64_e32 v[80:81], 0
	v_mov_b64_e32 v[82:83], 0
	v_mov_b64_e32 v[84:85], 0
	v_mov_b64_e32 v[86:87], 0
	v_mov_b64_e32 v[102:103], 0
	v_mov_b64_e32 v[104:105], 0
	v_mov_b64_e32 v[110:111], 0
	v_mov_b64_e32 v[112:113], 0
	v_mov_b64_e32 v[130:131], 0
	v_mov_b64_e32 v[132:133], 0
	v_mov_b64_e32 v[134:135], 0
	v_mov_b64_e32 v[136:137], 0
	v_mov_b64_e32 v[72:73], 0
	v_mov_b64_e32 v[74:75], 0
	v_mov_b64_e32 v[76:77], 0
	v_mov_b64_e32 v[78:79], 0
	v_mov_b64_e32 v[88:89], 0
	v_mov_b64_e32 v[90:91], 0
	v_mov_b64_e32 v[92:93], 0
	v_mov_b64_e32 v[94:95], 0
	v_mov_b64_e32 v[114:115], 0
	v_mov_b64_e32 v[116:117], 0
	v_mov_b64_e32 v[122:123], 0
	v_mov_b64_e32 v[124:125], 0
	v_mov_b64_e32 v[146:147], 0
	v_mov_b64_e32 v[148:149], 0
	v_mov_b64_e32 v[154:155], 0
	v_mov_b64_e32 v[156:157], 0

; template <class Epi, class Sched, bool ALIGN_EPI = false, bool SP2 = false>
; __device__ __forceinline__ void gemm_phase(PG8_LAS unsigned char* lds, const Gemm g, const Sched& S, const Epi& E) {
;     ...
; #pragma unroll
;         for (int a = 0; a < 2; ++a)
; #pragma unroll
;             for (int b = 0; b < 2; ++b)
; #pragma unroll
;                 for (int m = 0; m < 4; ++m)
; #pragma unroll
;                     for (int n = 0; n < 2; ++n) acc[a][b][m][n] = (f32x4){0.f, 0.f, 0.f, 0.f};
;         cur = nxt; cA = nA; cB = nB; ++ui;
.LBB0_509:
	s_add_u32 s45, s94, 0x100
	s_addc_u32 s94, s95, 0
	s_add_u32 s40, s96, 0x80
	v_mov_b32_e32 v0, 0
	s_addc_u32 s41, s97, 0
	s_mov_b32 s0, 0
	v_mov_b32_e32 v1, v0
	v_mov_b64_e32 v[2:3], 0
	v_mov_b64_e32 v[4:5], 0
	v_mov_b64_e32 v[6:7], 0
	v_mov_b64_e32 v[12:13], 0
	v_mov_b64_e32 v[14:15], 0
	v_mov_b64_e32 v[20:21], 0
	v_mov_b64_e32 v[22:23], 0
	v_mov_b64_e32 v[28:29], 0
	v_mov_b64_e32 v[30:31], 0
	v_mov_b64_e32 v[36:37], 0
	v_mov_b64_e32 v[38:39], 0
	v_mov_b64_e32 v[44:45], 0
	v_mov_b64_e32 v[46:47], 0
	v_mov_b64_e32 v[52:53], 0
	v_mov_b64_e32 v[54:55], 0
	v_mov_b64_e32 v[8:9], 0
	v_mov_b64_e32 v[10:11], 0
	v_mov_b64_e32 v[16:17], 0
	v_mov_b64_e32 v[18:19], 0
	v_mov_b64_e32 v[24:25], 0
	v_mov_b64_e32 v[26:27], 0
	v_mov_b64_e32 v[32:33], 0
	v_mov_b64_e32 v[34:35], 0
	v_mov_b64_e32 v[40:41], 0
	v_mov_b64_e32 v[42:43], 0
	v_mov_b64_e32 v[48:49], 0
	v_mov_b64_e32 v[50:51], 0
	v_mov_b64_e32 v[56:57], 0
	v_mov_b64_e32 v[58:59], 0
	v_mov_b64_e32 v[60:61], 0
	v_mov_b64_e32 v[62:63], 0
	v_mov_b64_e32 v[64:65], 0
	v_mov_b64_e32 v[66:67], 0
	v_mov_b64_e32 v[68:69], 0
	v_mov_b64_e32 v[70:71], 0
	v_mov_b64_e32 v[76:77], 0
	v_mov_b64_e32 v[78:79], 0
	v_mov_b64_e32 v[84:85], 0
	v_mov_b64_e32 v[86:87], 0
	v_mov_b64_e32 v[92:93], 0
	v_mov_b64_e32 v[94:95], 0
	v_mov_b64_e32 v[102:103], 0
	v_mov_b64_e32 v[104:105], 0
	v_mov_b64_e32 v[110:111], 0
	v_mov_b64_e32 v[112:113], 0
	v_mov_b64_e32 v[118:119], 0
	v_mov_b64_e32 v[120:121], 0
	v_mov_b64_e32 v[72:73], 0
	v_mov_b64_e32 v[74:75], 0
	v_mov_b64_e32 v[80:81], 0
	v_mov_b64_e32 v[82:83], 0
	v_mov_b64_e32 v[88:89], 0
	v_mov_b64_e32 v[90:91], 0
	v_mov_b64_e32 v[98:99], 0
	v_mov_b64_e32 v[100:101], 0
	v_mov_b64_e32 v[106:107], 0
	v_mov_b64_e32 v[108:109], 0
	v_mov_b64_e32 v[114:115], 0
	v_mov_b64_e32 v[116:117], 0
	v_mov_b64_e32 v[122:123], 0
	v_mov_b64_e32 v[124:125], 0
	v_mov_b64_e32 v[126:127], 0
	v_mov_b64_e32 v[128:129], 0
